# diff-attn: wave halves staggered by half a tile (two barriers per tile, per-half loop bodies)
# speedup vs baseline: 1.0283x; 1.0029x over previous
.LBB0_268:
	v_lshl_add_u64 v[158:159], v[154:155], 0, s[72:73]
	v_lshl_add_u64 v[156:157], v[152:153], 0, s[72:73]
	s_waitcnt vmcnt(3)
	ds_write_b128 v180, v[98:101]
	s_waitcnt vmcnt(2)
	ds_write_b128 v180, v[102:105] offset:8192
	s_waitcnt vmcnt(0)
	ds_write2st64_b64 v178, v[106:107], v[110:111] offset0:32 offset1:48
	ds_write2st64_b64 v179, v[108:109], v[112:113] offset0:32 offset1:48
	s_add_i32 s4, s64, -1
	s_cmp_ge_u32 s4, s18
	s_cbranch_scc1 .Ldg_nold1
	v_add_co_u32_e32 v64, vcc, 0xfff94000, v150
	s_nop 1
	v_addc_co_u32_e32 v65, vcc, -1, v151, vcc
	v_add_co_u32_e32 v208, vcc, 0xfffb8000, v150
	s_nop 1
	v_addc_co_u32_e32 v209, vcc, -1, v151, vcc
	global_load_dwordx4 v[98:101], v[64:65], off
	global_load_dwordx4 v[102:105], v[208:209], off
	v_add_co_u32_e32 v64, vcc, 0x2f800000, v158
	s_nop 1
	v_addc_co_u32_e32 v65, vcc, 0, v159, vcc
	global_load_dwordx4 v[106:109], v[64:65], off offset:384
	v_add_co_u32_e32 v64, vcc, 0x2f800000, v156
	s_nop 1
	v_addc_co_u32_e32 v65, vcc, 0, v157, vcc
	global_load_dwordx4 v[110:113], v[64:65], off offset:384
.Ldg_nold1:
	s_waitcnt lgkmcnt(0)
	s_barrier
	v_readfirstlane_b32 s4, v177
	s_nop 3
	s_lshr_b32 s4, s4, 6
	s_cmp_ge_u32 s4, 4
	s_cbranch_scc1 .Ldg_bpro
	ds_read_b128 v[114:117], v181
	ds_read_b128 v[118:121], v182
	ds_read_b128 v[122:125], v183
	ds_read_b128 v[126:129], v192
	ds_read_b128 v[142:145], v181 offset:8192
	ds_read_b128 v[138:141], v182 offset:8192
	ds_read_b128 v[134:137], v183 offset:8192
	ds_read_b128 v[130:133], v192 offset:8192
	s_sub_i32 s4, s68, 64
	s_cmp_le_i32 s4, s19
	s_cselect_b64 s[16:17], -1, 0
	s_cmp_gt_i32 s4, s19
	s_cselect_b64 vcc, -1, 0
	s_add_i32 s69, s65, s68
	s_add_i32 s4, s69, 0xffffffa1
	s_cmpk_gt_i32 s4, 0x7f
	s_cselect_b64 s[54:55], -1, 0
	s_and_b64 s[4:5], vcc, s[54:55]
	v_cndmask_b32_e64 v64, 0, v147, s[4:5]
	v_cndmask_b32_e32 v253, v146, v64, vcc
	s_or_b64 s[4:5], s[16:17], s[54:55]
	s_xor_b64 s[80:81], s[4:5], -1
	v_sub_f32_e32 v64, v253, v149
	v_cmp_ne_u32_e32 vcc, v64, v220
	s_cbranch_vccz .Ldg_ci2
	v_mov_b32_e32 v220, v64
	v_mov_b32_e32 v221, v64
	v_mov_b32_e32 v222, v64
	v_mov_b32_e32 v223, v64
	v_mov_b32_e32 v224, v64
	v_mov_b32_e32 v225, v64
	v_mov_b32_e32 v226, v64
	v_mov_b32_e32 v227, v64
	v_mov_b32_e32 v228, v64
	v_mov_b32_e32 v229, v64
	v_mov_b32_e32 v230, v64
	v_mov_b32_e32 v231, v64
	v_mov_b32_e32 v232, v64
	v_mov_b32_e32 v233, v64
	v_mov_b32_e32 v234, v64
	v_mov_b32_e32 v235, v64

.Ldg_back0_2:
	v_exp_f32_e32 v66, v66
	v_exp_f32_e32 v67, v67
	v_exp_f32_e32 v68, v68
	v_exp_f32_e32 v69, v69
	v_exp_f32_e32 v70, v70
	v_exp_f32_e32 v71, v71
	v_exp_f32_e32 v72, v72
	v_exp_f32_e32 v73, v73
	v_exp_f32_e32 v74, v74
	v_exp_f32_e32 v75, v75
	v_exp_f32_e32 v76, v76
	v_exp_f32_e32 v77, v77
	v_exp_f32_e32 v78, v78
	v_exp_f32_e32 v79, v79
	v_exp_f32_e32 v80, v80
	v_exp_f32_e32 v81, v81
	v_cvt_pk_bf16_f32 v200, v66, v67
	v_cvt_pk_bf16_f32 v201, v68, v69
	v_cvt_pk_bf16_f32 v202, v70, v71
	v_cvt_pk_bf16_f32 v203, v72, v73
	v_cvt_pk_bf16_f32 v204, v74, v75
	v_cvt_pk_bf16_f32 v205, v76, v77
	v_cvt_pk_bf16_f32 v206, v78, v79
	v_cvt_pk_bf16_f32 v207, v80, v81
	s_barrier
.Ldg_aloop:
	s_waitcnt lgkmcnt(7)
	v_mfma_f32_32x32x16_bf16 v[0:15], v[200:203], v[126:129], v[0:15]
	v_add_f32_e32 v168, v66, v67
	v_add_f32_e32 v169, v68, v69
	v_add_f32_e32 v170, v70, v71
	v_add_f32_e32 v171, v72, v73
	v_add_f32_e32 v172, v74, v75
	v_add_f32_e32 v173, v76, v77
	s_waitcnt lgkmcnt(6)
	v_mfma_f32_32x32x16_bf16 v[16:31], v[200:203], v[114:117], v[16:31]
	v_add_f32_e32 v174, v78, v79
	v_add_f32_e32 v175, v80, v81
	v_add_f32_e32 v168, v168, v169
	v_add_f32_e32 v170, v170, v171
	v_add_f32_e32 v172, v172, v173
	s_waitcnt lgkmcnt(5)
	v_mfma_f32_32x32x16_bf16 v[0:15], v[204:207], v[122:125], v[0:15]
	v_add_f32_e32 v174, v174, v175
	v_add_f32_e32 v168, v168, v170
	v_add_f32_e32 v172, v172, v174
	v_add_f32_e32 v168, v168, v172
	v_add_f32_e32 v184, v184, v168
	s_waitcnt lgkmcnt(4)
	v_mfma_f32_32x32x16_bf16 v[16:31], v[204:207], v[118:121], v[16:31]
	s_andn2_b64 vcc, exec, s[80:81]
	s_cbranch_vccnz .Ldg_nb1_3
	ds_read2_b32 v[160:161], v148 offset0:32 offset1:33
	ds_read2_b32 v[162:163], v148 offset0:34 offset1:35
	ds_read2_b32 v[164:165], v148 offset0:40 offset1:41
	ds_read2_b32 v[166:167], v148 offset0:42 offset1:43
	ds_read2_b32 v[168:169], v148 offset0:48 offset1:49
	ds_read2_b32 v[170:171], v148 offset0:50 offset1:51
	ds_read2_b32 v[172:173], v148 offset0:56 offset1:57
	ds_read2_b32 v[174:175], v148 offset0:58 offset1:59
	s_waitcnt lgkmcnt(7)
	v_pk_add_f32 v[236:237], v[236:237], v[160:161]
	s_waitcnt lgkmcnt(6)
	v_pk_add_f32 v[238:239], v[238:239], v[162:163]
	s_waitcnt lgkmcnt(5)
	v_pk_add_f32 v[240:241], v[240:241], v[164:165]
	s_waitcnt lgkmcnt(4)
	v_pk_add_f32 v[242:243], v[242:243], v[166:167]
	s_waitcnt lgkmcnt(3)
	v_pk_add_f32 v[244:245], v[244:245], v[168:169]
	s_waitcnt lgkmcnt(2)
	v_pk_add_f32 v[246:247], v[246:247], v[170:171]
	s_waitcnt lgkmcnt(1)
	v_pk_add_f32 v[248:249], v[248:249], v[172:173]
	s_waitcnt lgkmcnt(0)
	v_pk_add_f32 v[250:251], v[250:251], v[174:175]
	s_nop 0

; template <int KW, int DV, bool BIAS> ...
;     ...
;     for (int t = 0; t < NT; t += 2) { TILE(0, t); TILE(1, t + 1); }
.Ldg_join1_3:
	s_waitcnt lgkmcnt(3)
	v_mfma_f32_32x32x16_bf16 v[0:15], v[160:163], v[126:129], v[0:15]
	ds_read_b128 v[130:133], v195 offset:24576
	ds_read_b128 v[134:137], v195 offset:28672
	v_add_f32_e32 v168, v236, v237
	v_add_f32_e32 v169, v238, v239
	v_add_f32_e32 v170, v240, v241
	v_add_f32_e32 v171, v242, v243
	v_add_f32_e32 v172, v244, v245
	v_add_f32_e32 v173, v246, v247
	s_waitcnt lgkmcnt(4)
	v_mfma_f32_32x32x16_bf16 v[16:31], v[160:163], v[114:117], v[16:31]
	ds_read_b128 v[138:141], v196 offset:24576
	ds_read_b128 v[142:145], v196 offset:28672
	v_add_f32_e32 v174, v248, v249
	v_add_f32_e32 v175, v250, v251
	v_add_f32_e32 v168, v168, v169
	v_add_f32_e32 v170, v170, v171
	v_add_f32_e32 v172, v172, v173
	s_waitcnt lgkmcnt(5)
	v_mfma_f32_32x32x16_bf16 v[0:15], v[164:167], v[122:125], v[0:15]
	v_add_f32_e32 v174, v174, v175
	v_add_f32_e32 v168, v168, v170
	v_add_f32_e32 v172, v172, v174
	v_add_f32_e32 v168, v168, v172
	v_add_f32_e32 v184, v184, v168
	s_waitcnt lgkmcnt(4)
	v_mfma_f32_32x32x16_bf16 v[16:31], v[164:167], v[118:121], v[16:31]
	s_waitcnt lgkmcnt(3)
	v_mfma_f32_32x32x16_bf16 v[32:47], v[160:163], v[130:133], v[32:47]
	s_waitcnt lgkmcnt(2)
	v_mfma_f32_32x32x16_bf16 v[48:63], v[160:163], v[134:137], v[48:63]
	s_waitcnt lgkmcnt(1)
	v_mfma_f32_32x32x16_bf16 v[32:47], v[164:167], v[138:141], v[32:47]
	s_waitcnt lgkmcnt(0)
	v_mfma_f32_32x32x16_bf16 v[48:63], v[164:167], v[142:145], v[48:63]
	s_waitcnt vmcnt(3)
	ds_write_b128 v180, v[98:101] offset:32768
	s_waitcnt vmcnt(2)
	ds_write_b128 v180, v[102:105] offset:40960
	s_waitcnt vmcnt(0)
	ds_write2st64_b64 v178, v[106:107], v[110:111] offset0:96 offset1:112
	ds_write2st64_b64 v179, v[108:109], v[112:113] offset0:96 offset1:112
	s_cmp_ge_u32 s64, s18
	s_cbranch_scc1 .Ldg_nold4
	v_add_co_u32_e32 v64, vcc, 0xfffdc000, v150
	s_nop 1
	v_addc_co_u32_e32 v65, vcc, -1, v151, vcc
	global_load_dwordx4 v[98:101], v[64:65], off
	global_load_dwordx4 v[102:105], v[150:151], off
	v_add_co_u32_e32 v64, vcc, 0x2f800000, v158
	s_nop 1
	v_addc_co_u32_e32 v65, vcc, 0, v159, vcc
	global_load_dwordx4 v[106:109], v[64:65], off offset:512
	v_add_co_u32_e32 v64, vcc, 0x2f800000, v156
	s_nop 1
	v_addc_co_u32_e32 v65, vcc, 0, v157, vcc
	global_load_dwordx4 v[110:113], v[64:65], off offset:512
.Ldg_nold4:
	s_waitcnt lgkmcnt(0)
	s_barrier
	ds_read_b128 v[114:117], v181 offset:32768
	ds_read_b128 v[118:121], v182 offset:32768
	ds_read_b128 v[122:125], v183 offset:32768
	ds_read_b128 v[126:129], v192 offset:32768
	ds_read_b128 v[142:145], v181 offset:40960
	ds_read_b128 v[138:141], v182 offset:40960
	ds_read_b128 v[134:137], v183 offset:40960
	ds_read_b128 v[130:133], v192 offset:40960
	s_cmp_le_i32 s68, s19
	s_cselect_b64 s[54:55], -1, 0
	s_cmp_gt_i32 s68, s19
	s_cselect_b64 vcc, -1, 0
	s_add_i32 s69, s65, s68
	s_sub_i32 s4, s69, 31
	s_cmpk_gt_i32 s4, 0x7f
	s_cselect_b64 s[70:71], -1, 0
	s_and_b64 s[4:5], vcc, s[70:71]
	v_cndmask_b32_e64 v64, 0, v147, s[4:5]
	v_cndmask_b32_e32 v253, v146, v64, vcc
	s_or_b64 s[4:5], s[54:55], s[70:71]
	s_xor_b64 s[80:81], s[4:5], -1
	v_sub_f32_e32 v64, v253, v149
	v_cmp_ne_u32_e32 vcc, v64, v220
	s_cbranch_vccz .Ldg_ci5
	v_mov_b32_e32 v220, v64
	v_mov_b32_e32 v221, v64
	v_mov_b32_e32 v222, v64
	v_mov_b32_e32 v223, v64
	v_mov_b32_e32 v224, v64
	v_mov_b32_e32 v225, v64
	v_mov_b32_e32 v226, v64
	v_mov_b32_e32 v227, v64
	v_mov_b32_e32 v228, v64
	v_mov_b32_e32 v229, v64
	v_mov_b32_e32 v230, v64
	v_mov_b32_e32 v231, v64
	v_mov_b32_e32 v232, v64
	v_mov_b32_e32 v233, v64
	v_mov_b32_e32 v234, v64
	v_mov_b32_e32 v235, v64

.Ldg_back0_5:
	v_exp_f32_e32 v66, v66
	v_exp_f32_e32 v67, v67
	v_exp_f32_e32 v68, v68
	v_exp_f32_e32 v69, v69
	v_exp_f32_e32 v70, v70
	v_exp_f32_e32 v71, v71
	v_exp_f32_e32 v72, v72
	v_exp_f32_e32 v73, v73
	v_exp_f32_e32 v74, v74
	v_exp_f32_e32 v75, v75
	v_exp_f32_e32 v76, v76
	v_exp_f32_e32 v77, v77
	v_exp_f32_e32 v78, v78
	v_exp_f32_e32 v79, v79
	v_exp_f32_e32 v80, v80
	v_exp_f32_e32 v81, v81
	v_cvt_pk_bf16_f32 v200, v66, v67
	v_cvt_pk_bf16_f32 v201, v68, v69
	v_cvt_pk_bf16_f32 v202, v70, v71
	v_cvt_pk_bf16_f32 v203, v72, v73
	v_cvt_pk_bf16_f32 v204, v74, v75
	v_cvt_pk_bf16_f32 v205, v76, v77
	v_cvt_pk_bf16_f32 v206, v78, v79
	v_cvt_pk_bf16_f32 v207, v80, v81
	s_barrier
	s_waitcnt lgkmcnt(7)
	v_mfma_f32_32x32x16_bf16 v[0:15], v[200:203], v[126:129], v[0:15]
	v_add_f32_e32 v168, v66, v67
	v_add_f32_e32 v169, v68, v69
	v_add_f32_e32 v170, v70, v71
	v_add_f32_e32 v171, v72, v73
	v_add_f32_e32 v172, v74, v75
	v_add_f32_e32 v173, v76, v77
	s_waitcnt lgkmcnt(6)
	v_mfma_f32_32x32x16_bf16 v[16:31], v[200:203], v[114:117], v[16:31]
	v_add_f32_e32 v174, v78, v79
	v_add_f32_e32 v175, v80, v81
	v_add_f32_e32 v168, v168, v169
	v_add_f32_e32 v170, v170, v171
	v_add_f32_e32 v172, v172, v173
	s_waitcnt lgkmcnt(5)
	v_mfma_f32_32x32x16_bf16 v[0:15], v[204:207], v[122:125], v[0:15]
	v_add_f32_e32 v174, v174, v175
	v_add_f32_e32 v168, v168, v170
	v_add_f32_e32 v172, v172, v174
	v_add_f32_e32 v168, v168, v172
	v_add_f32_e32 v184, v184, v168
	s_waitcnt lgkmcnt(4)
	v_mfma_f32_32x32x16_bf16 v[16:31], v[204:207], v[118:121], v[16:31]
	s_andn2_b64 vcc, exec, s[80:81]
	s_cbranch_vccnz .Ldg_nb1_6
	ds_read2_b32 v[160:161], v148 offset0:96 offset1:97
	ds_read2_b32 v[162:163], v148 offset0:98 offset1:99
	ds_read2_b32 v[164:165], v148 offset0:104 offset1:105
	ds_read2_b32 v[166:167], v148 offset0:106 offset1:107
	ds_read2_b32 v[168:169], v148 offset0:112 offset1:113
	ds_read2_b32 v[170:171], v148 offset0:114 offset1:115
	ds_read2_b32 v[172:173], v148 offset0:120 offset1:121
	ds_read2_b32 v[174:175], v148 offset0:122 offset1:123
	s_waitcnt lgkmcnt(7)
	v_pk_add_f32 v[236:237], v[236:237], v[160:161]
	s_waitcnt lgkmcnt(6)
	v_pk_add_f32 v[238:239], v[238:239], v[162:163]
	s_waitcnt lgkmcnt(5)
	v_pk_add_f32 v[240:241], v[240:241], v[164:165]
	s_waitcnt lgkmcnt(4)
	v_pk_add_f32 v[242:243], v[242:243], v[166:167]
	s_waitcnt lgkmcnt(3)
	v_pk_add_f32 v[244:245], v[244:245], v[168:169]
	s_waitcnt lgkmcnt(2)
	v_pk_add_f32 v[246:247], v[246:247], v[170:171]
	s_waitcnt lgkmcnt(1)
	v_pk_add_f32 v[248:249], v[248:249], v[172:173]
	s_waitcnt lgkmcnt(0)
	v_pk_add_f32 v[250:251], v[250:251], v[174:175]
	s_nop 0

; template <int KW, int DV, bool BIAS> ...
;     ...
;     for (int t = 0; t < NT; t += 2) { TILE(0, t); TILE(1, t + 1); }
.Ldg_join1_6:
	s_waitcnt lgkmcnt(3)
	v_mfma_f32_32x32x16_bf16 v[0:15], v[160:163], v[126:129], v[0:15]
	ds_read_b128 v[130:133], v195 offset:57344
	ds_read_b128 v[134:137], v195 offset:61440
	v_add_f32_e32 v168, v236, v237
	v_add_f32_e32 v169, v238, v239
	v_add_f32_e32 v170, v240, v241
	v_add_f32_e32 v171, v242, v243
	v_add_f32_e32 v172, v244, v245
	v_add_f32_e32 v173, v246, v247
	s_waitcnt lgkmcnt(4)
	v_mfma_f32_32x32x16_bf16 v[16:31], v[160:163], v[114:117], v[16:31]
	ds_read_b128 v[138:141], v196 offset:57344
	ds_read_b128 v[142:145], v196 offset:61440
	v_add_f32_e32 v174, v248, v249
	v_add_f32_e32 v175, v250, v251
	v_add_f32_e32 v168, v168, v169
	v_add_f32_e32 v170, v170, v171
	v_add_f32_e32 v172, v172, v173
	s_waitcnt lgkmcnt(5)
	v_mfma_f32_32x32x16_bf16 v[0:15], v[164:167], v[122:125], v[0:15]
	v_add_f32_e32 v174, v174, v175
	v_add_f32_e32 v168, v168, v170
	v_add_f32_e32 v172, v172, v174
	v_add_f32_e32 v168, v168, v172
	v_add_f32_e32 v184, v184, v168
	s_waitcnt lgkmcnt(4)
	v_mfma_f32_32x32x16_bf16 v[16:31], v[164:167], v[118:121], v[16:31]
	s_waitcnt lgkmcnt(3)
	v_mfma_f32_32x32x16_bf16 v[32:47], v[160:163], v[130:133], v[32:47]
	s_waitcnt lgkmcnt(2)
	v_mfma_f32_32x32x16_bf16 v[48:63], v[160:163], v[134:137], v[48:63]
	s_waitcnt lgkmcnt(1)
	v_mfma_f32_32x32x16_bf16 v[32:47], v[164:167], v[138:141], v[32:47]
	s_waitcnt lgkmcnt(0)
	v_mfma_f32_32x32x16_bf16 v[48:63], v[164:167], v[142:145], v[48:63]
	s_cmp_ge_u32 s64, s18
	s_cbranch_scc1 .Ldg_aexit
	s_waitcnt vmcnt(3)
	ds_write_b128 v180, v[98:101]
	s_waitcnt vmcnt(2)
	ds_write_b128 v180, v[102:105] offset:8192
	s_waitcnt vmcnt(0)
	ds_write2st64_b64 v178, v[106:107], v[110:111] offset0:32 offset1:48
	ds_write2st64_b64 v179, v[108:109], v[112:113] offset0:32 offset1:48
	v_lshl_add_u64 v[150:151], v[150:151], 0, s[94:95]
	v_lshl_add_u64 v[152:153], v[152:153], 0, s[84:85]
	v_lshl_add_u64 v[154:155], v[154:155], 0, s[84:85]
	s_add_i32 s64, s64, 2
	v_lshl_add_u64 v[158:159], v[154:155], 0, s[72:73]
	v_lshl_add_u64 v[156:157], v[152:153], 0, s[72:73]
	s_add_i32 s4, s64, -1
	s_cmp_ge_u32 s4, s18
	s_cbranch_scc1 .Ldg_nold7
	v_add_co_u32_e32 v64, vcc, 0xfff94000, v150
	s_nop 1
	v_addc_co_u32_e32 v65, vcc, -1, v151, vcc
	v_add_co_u32_e32 v208, vcc, 0xfffb8000, v150
	s_nop 1
	v_addc_co_u32_e32 v209, vcc, -1, v151, vcc
	global_load_dwordx4 v[98:101], v[64:65], off
	global_load_dwordx4 v[102:105], v[208:209], off
	v_add_co_u32_e32 v64, vcc, 0x2f800000, v158
	s_nop 1
	v_addc_co_u32_e32 v65, vcc, 0, v159, vcc
	global_load_dwordx4 v[106:109], v[64:65], off offset:384
	v_add_co_u32_e32 v64, vcc, 0x2f800000, v156
	s_nop 1
	v_addc_co_u32_e32 v65, vcc, 0, v157, vcc
	global_load_dwordx4 v[110:113], v[64:65], off offset:384
.Ldg_nold7:
	s_waitcnt lgkmcnt(0)
	s_barrier
	v_add_u32_e32 v148, 0x200, v148
	s_addk_i32 s68, 0x80
	ds_read_b128 v[114:117], v181
	ds_read_b128 v[118:121], v182
	ds_read_b128 v[122:125], v183
	ds_read_b128 v[126:129], v192
	ds_read_b128 v[142:145], v181 offset:8192
	ds_read_b128 v[138:141], v182 offset:8192
	ds_read_b128 v[134:137], v183 offset:8192
	ds_read_b128 v[130:133], v192 offset:8192
	s_sub_i32 s4, s68, 64
	s_cmp_le_i32 s4, s19
	s_cselect_b64 s[16:17], -1, 0
	s_cmp_gt_i32 s4, s19
	s_cselect_b64 vcc, -1, 0
	s_add_i32 s69, s65, s68
	s_add_i32 s4, s69, 0xffffffa1
	s_cmpk_gt_i32 s4, 0x7f
	s_cselect_b64 s[54:55], -1, 0
	s_and_b64 s[4:5], vcc, s[54:55]
	v_cndmask_b32_e64 v64, 0, v147, s[4:5]
	v_cndmask_b32_e32 v253, v146, v64, vcc
	s_or_b64 s[4:5], s[16:17], s[54:55]
	s_xor_b64 s[80:81], s[4:5], -1
	v_sub_f32_e32 v64, v253, v149
	v_cmp_ne_u32_e32 vcc, v64, v220
	s_cbranch_vccz .Ldg_ci8
	v_mov_b32_e32 v220, v64
	v_mov_b32_e32 v221, v64
	v_mov_b32_e32 v222, v64
	v_mov_b32_e32 v223, v64
	v_mov_b32_e32 v224, v64
	v_mov_b32_e32 v225, v64
	v_mov_b32_e32 v226, v64
	v_mov_b32_e32 v227, v64
	v_mov_b32_e32 v228, v64
	v_mov_b32_e32 v229, v64
	v_mov_b32_e32 v230, v64
	v_mov_b32_e32 v231, v64
	v_mov_b32_e32 v232, v64
	v_mov_b32_e32 v233, v64
	v_mov_b32_e32 v234, v64
	v_mov_b32_e32 v235, v64

.Ldg_back0_8:
	v_exp_f32_e32 v66, v66
	v_exp_f32_e32 v67, v67
	v_exp_f32_e32 v68, v68
	v_exp_f32_e32 v69, v69
	v_exp_f32_e32 v70, v70
	v_exp_f32_e32 v71, v71
	v_exp_f32_e32 v72, v72
	v_exp_f32_e32 v73, v73
	v_exp_f32_e32 v74, v74
	v_exp_f32_e32 v75, v75
	v_exp_f32_e32 v76, v76
	v_exp_f32_e32 v77, v77
	v_exp_f32_e32 v78, v78
	v_exp_f32_e32 v79, v79
	v_exp_f32_e32 v80, v80
	v_exp_f32_e32 v81, v81
	v_cvt_pk_bf16_f32 v200, v66, v67
	v_cvt_pk_bf16_f32 v201, v68, v69
	v_cvt_pk_bf16_f32 v202, v70, v71
	v_cvt_pk_bf16_f32 v203, v72, v73
	v_cvt_pk_bf16_f32 v204, v74, v75
	v_cvt_pk_bf16_f32 v205, v76, v77
	v_cvt_pk_bf16_f32 v206, v78, v79
	v_cvt_pk_bf16_f32 v207, v80, v81
	s_barrier
	s_branch .Ldg_aloop
.Ldg_aexit:
	s_barrier
	s_barrier
	s_branch .Ldg_exit
.Ldg_bpro:
	s_barrier
.Ldg_bloop:
	ds_read_b128 v[114:117], v181
	ds_read_b128 v[118:121], v182
	ds_read_b128 v[122:125], v183
	ds_read_b128 v[126:129], v192
	ds_read_b128 v[142:145], v181 offset:8192
	ds_read_b128 v[138:141], v182 offset:8192
	ds_read_b128 v[134:137], v183 offset:8192
	ds_read_b128 v[130:133], v192 offset:8192
	s_sub_i32 s4, s68, 64
	s_cmp_le_i32 s4, s19
	s_cselect_b64 s[16:17], -1, 0
	s_cmp_gt_i32 s4, s19
	s_cselect_b64 vcc, -1, 0
	s_add_i32 s69, s65, s68
	s_add_i32 s4, s69, 0xffffffa1
	s_cmpk_gt_i32 s4, 0x7f
	s_cselect_b64 s[54:55], -1, 0
	s_and_b64 s[4:5], vcc, s[54:55]
	v_cndmask_b32_e64 v64, 0, v147, s[4:5]
	v_cndmask_b32_e32 v253, v146, v64, vcc
	s_or_b64 s[4:5], s[16:17], s[54:55]
	s_xor_b64 s[80:81], s[4:5], -1
	v_sub_f32_e32 v64, v253, v149
	v_cmp_ne_u32_e32 vcc, v64, v220
	s_cbranch_vccz .Ldg_ci9
	v_mov_b32_e32 v220, v64
	v_mov_b32_e32 v221, v64
	v_mov_b32_e32 v222, v64
	v_mov_b32_e32 v223, v64
	v_mov_b32_e32 v224, v64
	v_mov_b32_e32 v225, v64
	v_mov_b32_e32 v226, v64
	v_mov_b32_e32 v227, v64
	v_mov_b32_e32 v228, v64
	v_mov_b32_e32 v229, v64
	v_mov_b32_e32 v230, v64
	v_mov_b32_e32 v231, v64
	v_mov_b32_e32 v232, v64
	v_mov_b32_e32 v233, v64
	v_mov_b32_e32 v234, v64
	v_mov_b32_e32 v235, v64

.Ldg_back0_9:
	v_exp_f32_e32 v66, v66
	v_exp_f32_e32 v67, v67
	v_exp_f32_e32 v68, v68
	v_exp_f32_e32 v69, v69
	v_exp_f32_e32 v70, v70
	v_exp_f32_e32 v71, v71
	v_exp_f32_e32 v72, v72
	v_exp_f32_e32 v73, v73
	v_exp_f32_e32 v74, v74
	v_exp_f32_e32 v75, v75
	v_exp_f32_e32 v76, v76
	v_exp_f32_e32 v77, v77
	v_exp_f32_e32 v78, v78
	v_exp_f32_e32 v79, v79
	v_exp_f32_e32 v80, v80
	v_exp_f32_e32 v81, v81
	v_cvt_pk_bf16_f32 v200, v66, v67
	v_cvt_pk_bf16_f32 v201, v68, v69
	v_cvt_pk_bf16_f32 v202, v70, v71
	v_cvt_pk_bf16_f32 v203, v72, v73
	v_cvt_pk_bf16_f32 v204, v74, v75
	v_cvt_pk_bf16_f32 v205, v76, v77
	v_cvt_pk_bf16_f32 v206, v78, v79
	v_cvt_pk_bf16_f32 v207, v80, v81
	s_waitcnt vmcnt(3)
	ds_write_b128 v180, v[98:101] offset:32768
	s_waitcnt vmcnt(2)
	ds_write_b128 v180, v[102:105] offset:40960
	s_waitcnt vmcnt(0)
	ds_write2st64_b64 v178, v[106:107], v[110:111] offset0:96 offset1:112
	ds_write2st64_b64 v179, v[108:109], v[112:113] offset0:96 offset1:112
	s_cmp_ge_u32 s64, s18
	s_cbranch_scc1 .Ldg_nold10
	v_add_co_u32_e32 v64, vcc, 0xfffdc000, v150
	s_nop 1
	v_addc_co_u32_e32 v65, vcc, -1, v151, vcc
	global_load_dwordx4 v[98:101], v[64:65], off
	global_load_dwordx4 v[102:105], v[150:151], off
	v_add_co_u32_e32 v64, vcc, 0x2f800000, v158
	s_nop 1
	v_addc_co_u32_e32 v65, vcc, 0, v159, vcc
	global_load_dwordx4 v[106:109], v[64:65], off offset:512
	v_add_co_u32_e32 v64, vcc, 0x2f800000, v156
	s_nop 1
	v_addc_co_u32_e32 v65, vcc, 0, v157, vcc
	global_load_dwordx4 v[110:113], v[64:65], off offset:512
.Ldg_nold10:
	s_waitcnt lgkmcnt(0)
	s_barrier
	v_mfma_f32_32x32x16_bf16 v[0:15], v[200:203], v[126:129], v[0:15]
	v_add_f32_e32 v168, v66, v67
	v_add_f32_e32 v169, v68, v69
	v_add_f32_e32 v170, v70, v71
	v_add_f32_e32 v171, v72, v73
	v_add_f32_e32 v172, v74, v75
	v_add_f32_e32 v173, v76, v77
	v_mfma_f32_32x32x16_bf16 v[16:31], v[200:203], v[114:117], v[16:31]
	v_add_f32_e32 v174, v78, v79
	v_add_f32_e32 v175, v80, v81
	v_add_f32_e32 v168, v168, v169
	v_add_f32_e32 v170, v170, v171
	v_add_f32_e32 v172, v172, v173
	v_mfma_f32_32x32x16_bf16 v[0:15], v[204:207], v[122:125], v[0:15]
	v_add_f32_e32 v174, v174, v175
	v_add_f32_e32 v168, v168, v170
	v_add_f32_e32 v172, v172, v174
	v_add_f32_e32 v168, v168, v172
	v_add_f32_e32 v184, v184, v168
	v_mfma_f32_32x32x16_bf16 v[16:31], v[204:207], v[118:121], v[16:31]
	s_andn2_b64 vcc, exec, s[80:81]
	s_cbranch_vccnz .Ldg_nb1_11
	ds_read2_b32 v[160:161], v148 offset0:32 offset1:33
	ds_read2_b32 v[162:163], v148 offset0:34 offset1:35
	ds_read2_b32 v[164:165], v148 offset0:40 offset1:41
	ds_read2_b32 v[166:167], v148 offset0:42 offset1:43
	ds_read2_b32 v[168:169], v148 offset0:48 offset1:49
	ds_read2_b32 v[170:171], v148 offset0:50 offset1:51
	ds_read2_b32 v[172:173], v148 offset0:56 offset1:57
	ds_read2_b32 v[174:175], v148 offset0:58 offset1:59
	s_waitcnt lgkmcnt(7)
	v_pk_add_f32 v[236:237], v[236:237], v[160:161]
	s_waitcnt lgkmcnt(6)
	v_pk_add_f32 v[238:239], v[238:239], v[162:163]
	s_waitcnt lgkmcnt(5)
	v_pk_add_f32 v[240:241], v[240:241], v[164:165]
	s_waitcnt lgkmcnt(4)
	v_pk_add_f32 v[242:243], v[242:243], v[166:167]
	s_waitcnt lgkmcnt(3)
	v_pk_add_f32 v[244:245], v[244:245], v[168:169]
	s_waitcnt lgkmcnt(2)
	v_pk_add_f32 v[246:247], v[246:247], v[170:171]
	s_waitcnt lgkmcnt(1)
	v_pk_add_f32 v[248:249], v[248:249], v[172:173]
	s_waitcnt lgkmcnt(0)
	v_pk_add_f32 v[250:251], v[250:251], v[174:175]
	s_nop 0
; template <int KW, int DV, bool BIAS> ...
;     ...
;     for (int t = 0; t < NT; t += 2) { TILE(0, t); TILE(1, t + 1); }
.Ldg_nb1_11:
	v_max_f32_e32 v64, v237, v237
	v_max_f32_e32 v65, v236, v236
	v_max_f32_e32 v64, v65, v64
	v_max3_f32 v64, v64, v238, v239
	v_max3_f32 v64, v64, v240, v241
	v_max3_f32 v64, v64, v242, v243
	v_max3_f32 v64, v64, v244, v245
	v_max3_f32 v64, v64, v246, v247
	v_max3_f32 v64, v64, v248, v249
	v_max3_f32 v64, v64, v250, v251
	v_mov_b32_e32 v65, v64
	s_nop 1
	v_permlane32_swap_b32_e32 v64, v65
	v_max_f32_e32 v65, v65, v65
	v_max_f32_e32 v64, v64, v64
	v_max_f32_e32 v64, v64, v65
	v_cmp_lt_f32_e32 vcc, s97, v64
	s_cbranch_vccnz .Ldg_rare1_11
	v_mfma_f32_32x32x16_bf16 v[32:47], v[200:203], v[130:133], v[32:47]
	ds_read_b128 v[126:129], v195 offset:16384
	ds_read_b128 v[114:117], v195 offset:20480
	v_exp_f32_e32 v236, v236
	v_exp_f32_e32 v237, v237
	v_exp_f32_e32 v238, v238
	v_mfma_f32_32x32x16_bf16 v[48:63], v[200:203], v[134:137], v[48:63]
	ds_read_b128 v[122:125], v196 offset:16384
	ds_read_b128 v[118:121], v196 offset:20480
	v_exp_f32_e32 v239, v239
	v_exp_f32_e32 v240, v240
	v_exp_f32_e32 v241, v241
	v_mfma_f32_32x32x16_bf16 v[32:47], v[204:207], v[138:141], v[32:47]
	v_exp_f32_e32 v242, v242
	v_exp_f32_e32 v243, v243
	v_exp_f32_e32 v244, v244
	v_mfma_f32_32x32x16_bf16 v[48:63], v[204:207], v[142:145], v[48:63]
	v_exp_f32_e32 v245, v245
	v_exp_f32_e32 v246, v246
	v_exp_f32_e32 v247, v247
	v_exp_f32_e32 v248, v248
	v_exp_f32_e32 v249, v249
	v_exp_f32_e32 v250, v250
	v_exp_f32_e32 v251, v251
	v_cvt_pk_bf16_f32 v160, v236, v237
	v_cvt_pk_bf16_f32 v161, v238, v239
	v_cvt_pk_bf16_f32 v162, v240, v241
	v_cvt_pk_bf16_f32 v163, v242, v243
	v_cvt_pk_bf16_f32 v164, v244, v245
	v_cvt_pk_bf16_f32 v165, v246, v247
	v_cvt_pk_bf16_f32 v166, v248, v249
	v_cvt_pk_bf16_f32 v167, v250, v251
.Ldg_join1_11:
	s_waitcnt lgkmcnt(3)
	v_mfma_f32_32x32x16_bf16 v[0:15], v[160:163], v[126:129], v[0:15]
	ds_read_b128 v[130:133], v195 offset:24576
	ds_read_b128 v[134:137], v195 offset:28672
	v_add_f32_e32 v168, v236, v237
	v_add_f32_e32 v169, v238, v239
	v_add_f32_e32 v170, v240, v241
	v_add_f32_e32 v171, v242, v243
	v_add_f32_e32 v172, v244, v245
	v_add_f32_e32 v173, v246, v247
	s_waitcnt lgkmcnt(4)
	v_mfma_f32_32x32x16_bf16 v[16:31], v[160:163], v[114:117], v[16:31]
	ds_read_b128 v[138:141], v196 offset:24576
	ds_read_b128 v[142:145], v196 offset:28672
	v_add_f32_e32 v174, v248, v249
	v_add_f32_e32 v175, v250, v251
	v_add_f32_e32 v168, v168, v169
	v_add_f32_e32 v170, v170, v171
	v_add_f32_e32 v172, v172, v173
	s_waitcnt lgkmcnt(5)
	v_mfma_f32_32x32x16_bf16 v[0:15], v[164:167], v[122:125], v[0:15]
	v_add_f32_e32 v174, v174, v175
	v_add_f32_e32 v168, v168, v170
	v_add_f32_e32 v172, v172, v174
	v_add_f32_e32 v168, v168, v172
	v_add_f32_e32 v184, v184, v168
	s_waitcnt lgkmcnt(4)
	v_mfma_f32_32x32x16_bf16 v[16:31], v[164:167], v[118:121], v[16:31]
	s_waitcnt lgkmcnt(3)
	v_mfma_f32_32x32x16_bf16 v[32:47], v[160:163], v[130:133], v[32:47]
	s_waitcnt lgkmcnt(2)
	v_mfma_f32_32x32x16_bf16 v[48:63], v[160:163], v[134:137], v[48:63]
	s_waitcnt lgkmcnt(1)
	v_mfma_f32_32x32x16_bf16 v[32:47], v[164:167], v[138:141], v[32:47]
	s_waitcnt lgkmcnt(0)
	v_mfma_f32_32x32x16_bf16 v[48:63], v[164:167], v[142:145], v[48:63]
	s_barrier
	ds_read_b128 v[114:117], v181 offset:32768
	ds_read_b128 v[118:121], v182 offset:32768
	ds_read_b128 v[122:125], v183 offset:32768
	ds_read_b128 v[126:129], v192 offset:32768
	ds_read_b128 v[142:145], v181 offset:40960
	ds_read_b128 v[138:141], v182 offset:40960
	ds_read_b128 v[134:137], v183 offset:40960
	ds_read_b128 v[130:133], v192 offset:40960
	s_cmp_le_i32 s68, s19
	s_cselect_b64 s[54:55], -1, 0
	s_cmp_gt_i32 s68, s19
	s_cselect_b64 vcc, -1, 0
	s_add_i32 s69, s65, s68
	s_sub_i32 s4, s69, 31
	s_cmpk_gt_i32 s4, 0x7f
	s_cselect_b64 s[70:71], -1, 0
	s_and_b64 s[4:5], vcc, s[70:71]
	v_cndmask_b32_e64 v64, 0, v147, s[4:5]
	v_cndmask_b32_e32 v253, v146, v64, vcc
	s_or_b64 s[4:5], s[54:55], s[70:71]
	s_xor_b64 s[80:81], s[4:5], -1
	v_sub_f32_e32 v64, v253, v149
	v_cmp_ne_u32_e32 vcc, v64, v220
	s_cbranch_vccz .Ldg_ci12
	v_mov_b32_e32 v220, v64
	v_mov_b32_e32 v221, v64
	v_mov_b32_e32 v222, v64
	v_mov_b32_e32 v223, v64
	v_mov_b32_e32 v224, v64
	v_mov_b32_e32 v225, v64
	v_mov_b32_e32 v226, v64
	v_mov_b32_e32 v227, v64
	v_mov_b32_e32 v228, v64
	v_mov_b32_e32 v229, v64
	v_mov_b32_e32 v230, v64
	v_mov_b32_e32 v231, v64
	v_mov_b32_e32 v232, v64
	v_mov_b32_e32 v233, v64
	v_mov_b32_e32 v234, v64
	v_mov_b32_e32 v235, v64

.Ldg_back0_12:
	v_exp_f32_e32 v66, v66
	v_exp_f32_e32 v67, v67
	v_exp_f32_e32 v68, v68
	v_exp_f32_e32 v69, v69
	v_exp_f32_e32 v70, v70
	v_exp_f32_e32 v71, v71
	v_exp_f32_e32 v72, v72
	v_exp_f32_e32 v73, v73
	v_exp_f32_e32 v74, v74
	v_exp_f32_e32 v75, v75
	v_exp_f32_e32 v76, v76
	v_exp_f32_e32 v77, v77
	v_exp_f32_e32 v78, v78
	v_exp_f32_e32 v79, v79
	v_exp_f32_e32 v80, v80
	v_exp_f32_e32 v81, v81
	v_cvt_pk_bf16_f32 v200, v66, v67
	v_cvt_pk_bf16_f32 v201, v68, v69
	v_cvt_pk_bf16_f32 v202, v70, v71
	v_cvt_pk_bf16_f32 v203, v72, v73
	v_cvt_pk_bf16_f32 v204, v74, v75
	v_cvt_pk_bf16_f32 v205, v76, v77
	v_cvt_pk_bf16_f32 v206, v78, v79
	v_cvt_pk_bf16_f32 v207, v80, v81
	s_waitcnt vmcnt(3)
	ds_write_b128 v180, v[98:101]
	s_waitcnt vmcnt(2)
	ds_write_b128 v180, v[102:105] offset:8192
	s_waitcnt vmcnt(0)
	ds_write2st64_b64 v178, v[106:107], v[110:111] offset0:32 offset1:48
	ds_write2st64_b64 v179, v[108:109], v[112:113] offset0:32 offset1:48
	v_lshl_add_u64 v[150:151], v[150:151], 0, s[94:95]
	v_lshl_add_u64 v[152:153], v[152:153], 0, s[84:85]
	v_lshl_add_u64 v[154:155], v[154:155], 0, s[84:85]
	s_add_i32 s64, s64, 2
	v_lshl_add_u64 v[158:159], v[154:155], 0, s[72:73]
	v_lshl_add_u64 v[156:157], v[152:153], 0, s[72:73]
	s_add_i32 s4, s64, -1
	s_cmp_ge_u32 s4, s18
	s_cbranch_scc1 .Ldg_nold13
	v_add_co_u32_e32 v64, vcc, 0xfff94000, v150
	s_nop 1
	v_addc_co_u32_e32 v65, vcc, -1, v151, vcc
	v_add_co_u32_e32 v208, vcc, 0xfffb8000, v150
	s_nop 1
	v_addc_co_u32_e32 v209, vcc, -1, v151, vcc
	global_load_dwordx4 v[98:101], v[64:65], off
	global_load_dwordx4 v[102:105], v[208:209], off
	v_add_co_u32_e32 v64, vcc, 0x2f800000, v158
	s_nop 1
	v_addc_co_u32_e32 v65, vcc, 0, v159, vcc
	global_load_dwordx4 v[106:109], v[64:65], off offset:384
	v_add_co_u32_e32 v64, vcc, 0x2f800000, v156
	s_nop 1
	v_addc_co_u32_e32 v65, vcc, 0, v157, vcc
	global_load_dwordx4 v[110:113], v[64:65], off offset:384
.Ldg_nold13:
	s_waitcnt lgkmcnt(0)
	s_barrier
	v_mfma_f32_32x32x16_bf16 v[0:15], v[200:203], v[126:129], v[0:15]
	v_add_f32_e32 v168, v66, v67
	v_add_f32_e32 v169, v68, v69
	v_add_f32_e32 v170, v70, v71
	v_add_f32_e32 v171, v72, v73
	v_add_f32_e32 v172, v74, v75
	v_add_f32_e32 v173, v76, v77
	v_mfma_f32_32x32x16_bf16 v[16:31], v[200:203], v[114:117], v[16:31]
	v_add_f32_e32 v174, v78, v79
	v_add_f32_e32 v175, v80, v81
	v_add_f32_e32 v168, v168, v169
	v_add_f32_e32 v170, v170, v171
	v_add_f32_e32 v172, v172, v173
	v_mfma_f32_32x32x16_bf16 v[0:15], v[204:207], v[122:125], v[0:15]
	v_add_f32_e32 v174, v174, v175
	v_add_f32_e32 v168, v168, v170
	v_add_f32_e32 v172, v172, v174
	v_add_f32_e32 v168, v168, v172
	v_add_f32_e32 v184, v184, v168
	v_mfma_f32_32x32x16_bf16 v[16:31], v[204:207], v[118:121], v[16:31]
	s_andn2_b64 vcc, exec, s[80:81]
	s_cbranch_vccnz .Ldg_nb1_14
	ds_read2_b32 v[160:161], v148 offset0:96 offset1:97
	ds_read2_b32 v[162:163], v148 offset0:98 offset1:99
	ds_read2_b32 v[164:165], v148 offset0:104 offset1:105
	ds_read2_b32 v[166:167], v148 offset0:106 offset1:107
	ds_read2_b32 v[168:169], v148 offset0:112 offset1:113
	ds_read2_b32 v[170:171], v148 offset0:114 offset1:115
	ds_read2_b32 v[172:173], v148 offset0:120 offset1:121
	ds_read2_b32 v[174:175], v148 offset0:122 offset1:123
	s_waitcnt lgkmcnt(7)
	v_pk_add_f32 v[236:237], v[236:237], v[160:161]
	s_waitcnt lgkmcnt(6)
	v_pk_add_f32 v[238:239], v[238:239], v[162:163]
	s_waitcnt lgkmcnt(5)
	v_pk_add_f32 v[240:241], v[240:241], v[164:165]
	s_waitcnt lgkmcnt(4)
	v_pk_add_f32 v[242:243], v[242:243], v[166:167]
	s_waitcnt lgkmcnt(3)
	v_pk_add_f32 v[244:245], v[244:245], v[168:169]
	s_waitcnt lgkmcnt(2)
	v_pk_add_f32 v[246:247], v[246:247], v[170:171]
	s_waitcnt lgkmcnt(1)
	v_pk_add_f32 v[248:249], v[248:249], v[172:173]
	s_waitcnt lgkmcnt(0)
	v_pk_add_f32 v[250:251], v[250:251], v[174:175]
	s_nop 0
; template <int KW, int DV, bool BIAS> ...
;     ...
;     for (int t = 0; t < NT; t += 2) { TILE(0, t); TILE(1, t + 1); }
.Ldg_nb1_14:
	v_max_f32_e32 v64, v237, v237
	v_max_f32_e32 v65, v236, v236
	v_max_f32_e32 v64, v65, v64
	v_max3_f32 v64, v64, v238, v239
	v_max3_f32 v64, v64, v240, v241
	v_max3_f32 v64, v64, v242, v243
	v_max3_f32 v64, v64, v244, v245
	v_max3_f32 v64, v64, v246, v247
	v_max3_f32 v64, v64, v248, v249
	v_max3_f32 v64, v64, v250, v251
	v_mov_b32_e32 v65, v64
	s_nop 1
	v_permlane32_swap_b32_e32 v64, v65
	v_max_f32_e32 v65, v65, v65
	v_max_f32_e32 v64, v64, v64
	v_max_f32_e32 v64, v64, v65
	v_cmp_lt_f32_e32 vcc, s97, v64
	s_cbranch_vccnz .Ldg_rare1_14
	v_mfma_f32_32x32x16_bf16 v[32:47], v[200:203], v[130:133], v[32:47]
	ds_read_b128 v[126:129], v195 offset:49152
	ds_read_b128 v[114:117], v195 offset:53248
	v_exp_f32_e32 v236, v236
	v_exp_f32_e32 v237, v237
	v_exp_f32_e32 v238, v238
	v_mfma_f32_32x32x16_bf16 v[48:63], v[200:203], v[134:137], v[48:63]
	ds_read_b128 v[122:125], v196 offset:49152
	ds_read_b128 v[118:121], v196 offset:53248
	v_exp_f32_e32 v239, v239
	v_exp_f32_e32 v240, v240
	v_exp_f32_e32 v241, v241
	v_mfma_f32_32x32x16_bf16 v[32:47], v[204:207], v[138:141], v[32:47]
	v_exp_f32_e32 v242, v242
	v_exp_f32_e32 v243, v243
	v_exp_f32_e32 v244, v244
	v_mfma_f32_32x32x16_bf16 v[48:63], v[204:207], v[142:145], v[48:63]
	v_exp_f32_e32 v245, v245
	v_exp_f32_e32 v246, v246
	v_exp_f32_e32 v247, v247
	v_exp_f32_e32 v248, v248
	v_exp_f32_e32 v249, v249
	v_exp_f32_e32 v250, v250
	v_exp_f32_e32 v251, v251
	v_cvt_pk_bf16_f32 v160, v236, v237
	v_cvt_pk_bf16_f32 v161, v238, v239
	v_cvt_pk_bf16_f32 v162, v240, v241
	v_cvt_pk_bf16_f32 v163, v242, v243
	v_cvt_pk_bf16_f32 v164, v244, v245
	v_cvt_pk_bf16_f32 v165, v246, v247
	v_cvt_pk_bf16_f32 v166, v248, v249
	v_cvt_pk_bf16_f32 v167, v250, v251
.Ldg_join1_14:
	s_waitcnt lgkmcnt(3)
	v_mfma_f32_32x32x16_bf16 v[0:15], v[160:163], v[126:129], v[0:15]
	ds_read_b128 v[130:133], v195 offset:57344
	ds_read_b128 v[134:137], v195 offset:61440
	v_add_f32_e32 v168, v236, v237
	v_add_f32_e32 v169, v238, v239
	v_add_f32_e32 v170, v240, v241
	v_add_f32_e32 v171, v242, v243
	v_add_f32_e32 v172, v244, v245
	v_add_f32_e32 v173, v246, v247
	s_waitcnt lgkmcnt(4)
	v_mfma_f32_32x32x16_bf16 v[16:31], v[160:163], v[114:117], v[16:31]
	ds_read_b128 v[138:141], v196 offset:57344
	ds_read_b128 v[142:145], v196 offset:61440
	v_add_f32_e32 v174, v248, v249
	v_add_f32_e32 v175, v250, v251
	v_add_f32_e32 v168, v168, v169
	v_add_f32_e32 v170, v170, v171
	v_add_f32_e32 v172, v172, v173
	s_waitcnt lgkmcnt(5)
	v_mfma_f32_32x32x16_bf16 v[0:15], v[164:167], v[122:125], v[0:15]
	v_add_f32_e32 v174, v174, v175
	v_add_f32_e32 v168, v168, v170
	v_add_f32_e32 v172, v172, v174
	v_add_f32_e32 v168, v168, v172
	v_add_f32_e32 v184, v184, v168
	s_waitcnt lgkmcnt(4)
	v_mfma_f32_32x32x16_bf16 v[16:31], v[164:167], v[118:121], v[16:31]
	s_waitcnt lgkmcnt(3)
	v_mfma_f32_32x32x16_bf16 v[32:47], v[160:163], v[130:133], v[32:47]
	s_waitcnt lgkmcnt(2)
	v_mfma_f32_32x32x16_bf16 v[48:63], v[160:163], v[134:137], v[48:63]
	s_waitcnt lgkmcnt(1)
	v_mfma_f32_32x32x16_bf16 v[32:47], v[164:167], v[138:141], v[32:47]
	s_waitcnt lgkmcnt(0)
	v_mfma_f32_32x32x16_bf16 v[48:63], v[164:167], v[142:145], v[48:63]
	s_barrier
	v_add_u32_e32 v148, 0x200, v148
	s_addk_i32 s68, 0x80
	s_cmp_gt_u32 s64, s18
	s_cbranch_scc0 .Ldg_bloop
	s_branch .Ldg_exit

.Ldg_rare1_6:
	s_waitcnt lgkmcnt(0)
	v_mfma_f32_32x32x16_bf16 v[32:47], v[200:203], v[130:133], v[32:47]
	v_mfma_f32_32x32x16_bf16 v[48:63], v[200:203], v[134:137], v[48:63]
	v_mfma_f32_32x32x16_bf16 v[32:47], v[204:207], v[138:141], v[32:47]
	v_mfma_f32_32x32x16_bf16 v[48:63], v[204:207], v[142:145], v[48:63]
	s_nop 15
	v_max_f32_e32 v65, v64, v64
	v_max_f32_e32 v65, 0, v65
	v_add_f32_e32 v149, v149, v65
	v_sub_f32_e32 v236, v236, v65
	v_sub_f32_e32 v237, v237, v65
	v_sub_f32_e32 v238, v238, v65
	v_sub_f32_e32 v239, v239, v65
	v_sub_f32_e32 v240, v240, v65
	v_sub_f32_e32 v241, v241, v65
	v_sub_f32_e32 v242, v242, v65
	v_sub_f32_e32 v243, v243, v65
	v_sub_f32_e32 v244, v244, v65
	v_sub_f32_e32 v245, v245, v65
	v_sub_f32_e32 v246, v246, v65
	v_sub_f32_e32 v247, v247, v65
	v_sub_f32_e32 v248, v248, v65
	v_sub_f32_e32 v249, v249, v65
	v_sub_f32_e32 v250, v250, v65
	v_sub_f32_e32 v251, v251, v65
	v_exp_f32_e64 v64, -v65
	s_nop 0
	ds_write_b32 v198, v64
	ds_read_b128 v[160:163], v197
	ds_read_b128 v[164:167], v197 offset:32
	ds_read_b128 v[168:171], v197 offset:64
	ds_read_b128 v[172:175], v197 offset:96
	v_mul_f32_e32 v184, v184, v64
	s_waitcnt lgkmcnt(0)
	v_pk_mul_f32 v[0:1], v[0:1], v[160:161]
	v_pk_mul_f32 v[2:3], v[2:3], v[162:163]
	v_pk_mul_f32 v[4:5], v[4:5], v[164:165]
	v_pk_mul_f32 v[6:7], v[6:7], v[166:167]
	v_pk_mul_f32 v[8:9], v[8:9], v[168:169]
	v_pk_mul_f32 v[10:11], v[10:11], v[170:171]
	v_pk_mul_f32 v[12:13], v[12:13], v[172:173]
	v_pk_mul_f32 v[14:15], v[14:15], v[174:175]
	v_pk_mul_f32 v[16:17], v[16:17], v[160:161]
	v_pk_mul_f32 v[18:19], v[18:19], v[162:163]
	v_pk_mul_f32 v[20:21], v[20:21], v[164:165]
	v_pk_mul_f32 v[22:23], v[22:23], v[166:167]
	v_pk_mul_f32 v[24:25], v[24:25], v[168:169]
	v_pk_mul_f32 v[26:27], v[26:27], v[170:171]
	v_pk_mul_f32 v[28:29], v[28:29], v[172:173]
	v_pk_mul_f32 v[30:31], v[30:31], v[174:175]
	v_pk_mul_f32 v[32:33], v[32:33], v[160:161]
	v_pk_mul_f32 v[34:35], v[34:35], v[162:163]
	v_pk_mul_f32 v[36:37], v[36:37], v[164:165]
	v_pk_mul_f32 v[38:39], v[38:39], v[166:167]
	v_pk_mul_f32 v[40:41], v[40:41], v[168:169]
	v_pk_mul_f32 v[42:43], v[42:43], v[170:171]
	v_pk_mul_f32 v[44:45], v[44:45], v[172:173]
	v_pk_mul_f32 v[46:47], v[46:47], v[174:175]
	v_pk_mul_f32 v[48:49], v[48:49], v[160:161]
	v_pk_mul_f32 v[50:51], v[50:51], v[162:163]
	v_pk_mul_f32 v[52:53], v[52:53], v[164:165]
	v_pk_mul_f32 v[54:55], v[54:55], v[166:167]
	v_pk_mul_f32 v[56:57], v[56:57], v[168:169]
	v_pk_mul_f32 v[58:59], v[58:59], v[170:171]
	v_pk_mul_f32 v[60:61], v[60:61], v[172:173]
	v_pk_mul_f32 v[62:63], v[62:63], v[174:175]
	ds_read_b128 v[126:129], v195 offset:49152
	ds_read_b128 v[114:117], v195 offset:53248
	ds_read_b128 v[122:125], v196 offset:49152
	ds_read_b128 v[118:121], v196 offset:53248
	v_exp_f32_e32 v236, v236
	v_exp_f32_e32 v237, v237
	v_exp_f32_e32 v238, v238
	v_exp_f32_e32 v239, v239
	v_exp_f32_e32 v240, v240
	v_exp_f32_e32 v241, v241
	v_exp_f32_e32 v242, v242
	v_exp_f32_e32 v243, v243
	v_exp_f32_e32 v244, v244
	v_exp_f32_e32 v245, v245
	v_exp_f32_e32 v246, v246
	v_exp_f32_e32 v247, v247
	v_exp_f32_e32 v248, v248
	v_exp_f32_e32 v249, v249
	v_exp_f32_e32 v250, v250
	v_exp_f32_e32 v251, v251
	v_cvt_pk_bf16_f32 v160, v236, v237
	v_cvt_pk_bf16_f32 v161, v238, v239
	v_cvt_pk_bf16_f32 v162, v240, v241
	v_cvt_pk_bf16_f32 v163, v242, v243
	v_cvt_pk_bf16_f32 v164, v244, v245
	v_cvt_pk_bf16_f32 v165, v246, v247
	v_cvt_pk_bf16_f32 v166, v248, v249
	v_cvt_pk_bf16_f32 v167, v250, v251
	s_branch .Ldg_join1_6
.Ldg_rare0_8:
	s_nop 15
	v_max_f32_e32 v65, v64, v64
	v_max_f32_e32 v65, 0, v65
	v_add_f32_e32 v149, v149, v65
	v_sub_f32_e32 v66, v66, v65
	v_sub_f32_e32 v67, v67, v65
	v_sub_f32_e32 v68, v68, v65
	v_sub_f32_e32 v69, v69, v65
	v_sub_f32_e32 v70, v70, v65
	v_sub_f32_e32 v71, v71, v65
	v_sub_f32_e32 v72, v72, v65
	v_sub_f32_e32 v73, v73, v65
	v_sub_f32_e32 v74, v74, v65
	v_sub_f32_e32 v75, v75, v65
	v_sub_f32_e32 v76, v76, v65
	v_sub_f32_e32 v77, v77, v65
	v_sub_f32_e32 v78, v78, v65
	v_sub_f32_e32 v79, v79, v65
	v_sub_f32_e32 v80, v80, v65
	v_sub_f32_e32 v81, v81, v65
	v_sub_f32_e32 v236, v236, v65
	v_sub_f32_e32 v237, v237, v65
	v_sub_f32_e32 v238, v238, v65
	v_sub_f32_e32 v239, v239, v65
	v_sub_f32_e32 v240, v240, v65
	v_sub_f32_e32 v241, v241, v65
	v_sub_f32_e32 v242, v242, v65
	v_sub_f32_e32 v243, v243, v65
	v_sub_f32_e32 v244, v244, v65
	v_sub_f32_e32 v245, v245, v65
	v_sub_f32_e32 v246, v246, v65
	v_sub_f32_e32 v247, v247, v65
	v_sub_f32_e32 v248, v248, v65
	v_sub_f32_e32 v249, v249, v65
	v_sub_f32_e32 v250, v250, v65
	v_sub_f32_e32 v251, v251, v65
	v_exp_f32_e64 v64, -v65
	s_nop 0
	ds_write_b32 v198, v64
	ds_read_b128 v[160:163], v197
	ds_read_b128 v[164:167], v197 offset:32
	ds_read_b128 v[168:171], v197 offset:64
	ds_read_b128 v[172:175], v197 offset:96
	v_mul_f32_e32 v184, v184, v64
	s_waitcnt lgkmcnt(0)
	v_pk_mul_f32 v[0:1], v[0:1], v[160:161]
	v_pk_mul_f32 v[2:3], v[2:3], v[162:163]
	v_pk_mul_f32 v[4:5], v[4:5], v[164:165]
	v_pk_mul_f32 v[6:7], v[6:7], v[166:167]
	v_pk_mul_f32 v[8:9], v[8:9], v[168:169]
	v_pk_mul_f32 v[10:11], v[10:11], v[170:171]
	v_pk_mul_f32 v[12:13], v[12:13], v[172:173]
	v_pk_mul_f32 v[14:15], v[14:15], v[174:175]
	v_pk_mul_f32 v[16:17], v[16:17], v[160:161]
	v_pk_mul_f32 v[18:19], v[18:19], v[162:163]
	v_pk_mul_f32 v[20:21], v[20:21], v[164:165]
	v_pk_mul_f32 v[22:23], v[22:23], v[166:167]
	v_pk_mul_f32 v[24:25], v[24:25], v[168:169]
	v_pk_mul_f32 v[26:27], v[26:27], v[170:171]
	v_pk_mul_f32 v[28:29], v[28:29], v[172:173]
	v_pk_mul_f32 v[30:31], v[30:31], v[174:175]
	v_pk_mul_f32 v[32:33], v[32:33], v[160:161]
	v_pk_mul_f32 v[34:35], v[34:35], v[162:163]
	v_pk_mul_f32 v[36:37], v[36:37], v[164:165]
	v_pk_mul_f32 v[38:39], v[38:39], v[166:167]
	v_pk_mul_f32 v[40:41], v[40:41], v[168:169]
	v_pk_mul_f32 v[42:43], v[42:43], v[170:171]
	v_pk_mul_f32 v[44:45], v[44:45], v[172:173]
	v_pk_mul_f32 v[46:47], v[46:47], v[174:175]
	v_pk_mul_f32 v[48:49], v[48:49], v[160:161]
	v_pk_mul_f32 v[50:51], v[50:51], v[162:163]
	v_pk_mul_f32 v[52:53], v[52:53], v[164:165]
	v_pk_mul_f32 v[54:55], v[54:55], v[166:167]
	v_pk_mul_f32 v[56:57], v[56:57], v[168:169]
	v_pk_mul_f32 v[58:59], v[58:59], v[170:171]
	v_pk_mul_f32 v[60:61], v[60:61], v[172:173]
	v_pk_mul_f32 v[62:63], v[62:63], v[174:175]
	v_sub_f32_e32 v64, v253, v149
	v_mov_b32_e32 v220, v64
	v_mov_b32_e32 v221, v64
	v_mov_b32_e32 v222, v64
	v_mov_b32_e32 v223, v64
	v_mov_b32_e32 v224, v64
	v_mov_b32_e32 v225, v64
	v_mov_b32_e32 v226, v64
	v_mov_b32_e32 v227, v64
	v_mov_b32_e32 v228, v64
	v_mov_b32_e32 v229, v64
	v_mov_b32_e32 v230, v64
	v_mov_b32_e32 v231, v64
	v_mov_b32_e32 v232, v64
	v_mov_b32_e32 v233, v64
	v_mov_b32_e32 v234, v64
	v_mov_b32_e32 v235, v64
	s_branch .Ldg_back0_8
.Ldg_rare0_9:
	s_nop 15
	v_max_f32_e32 v65, v64, v64
	v_max_f32_e32 v65, 0, v65
	v_add_f32_e32 v149, v149, v65
	v_sub_f32_e32 v66, v66, v65
	v_sub_f32_e32 v67, v67, v65
	v_sub_f32_e32 v68, v68, v65
	v_sub_f32_e32 v69, v69, v65
	v_sub_f32_e32 v70, v70, v65
	v_sub_f32_e32 v71, v71, v65
	v_sub_f32_e32 v72, v72, v65
	v_sub_f32_e32 v73, v73, v65
	v_sub_f32_e32 v74, v74, v65
	v_sub_f32_e32 v75, v75, v65
	v_sub_f32_e32 v76, v76, v65
	v_sub_f32_e32 v77, v77, v65
	v_sub_f32_e32 v78, v78, v65
	v_sub_f32_e32 v79, v79, v65
	v_sub_f32_e32 v80, v80, v65
	v_sub_f32_e32 v81, v81, v65
	v_sub_f32_e32 v236, v236, v65
	v_sub_f32_e32 v237, v237, v65
	v_sub_f32_e32 v238, v238, v65
	v_sub_f32_e32 v239, v239, v65
	v_sub_f32_e32 v240, v240, v65
	v_sub_f32_e32 v241, v241, v65
	v_sub_f32_e32 v242, v242, v65
	v_sub_f32_e32 v243, v243, v65
	v_sub_f32_e32 v244, v244, v65
	v_sub_f32_e32 v245, v245, v65
	v_sub_f32_e32 v246, v246, v65
	v_sub_f32_e32 v247, v247, v65
	v_sub_f32_e32 v248, v248, v65
	v_sub_f32_e32 v249, v249, v65
	v_sub_f32_e32 v250, v250, v65
	v_sub_f32_e32 v251, v251, v65
	v_exp_f32_e64 v64, -v65
	s_nop 0
	ds_write_b32 v198, v64
	ds_read_b128 v[160:163], v197
	ds_read_b128 v[164:167], v197 offset:32
	ds_read_b128 v[168:171], v197 offset:64
	ds_read_b128 v[172:175], v197 offset:96
	v_mul_f32_e32 v184, v184, v64
	s_waitcnt lgkmcnt(0)
	v_pk_mul_f32 v[0:1], v[0:1], v[160:161]
	v_pk_mul_f32 v[2:3], v[2:3], v[162:163]
	v_pk_mul_f32 v[4:5], v[4:5], v[164:165]
	v_pk_mul_f32 v[6:7], v[6:7], v[166:167]
	v_pk_mul_f32 v[8:9], v[8:9], v[168:169]
	v_pk_mul_f32 v[10:11], v[10:11], v[170:171]
	v_pk_mul_f32 v[12:13], v[12:13], v[172:173]
	v_pk_mul_f32 v[14:15], v[14:15], v[174:175]
	v_pk_mul_f32 v[16:17], v[16:17], v[160:161]
	v_pk_mul_f32 v[18:19], v[18:19], v[162:163]
	v_pk_mul_f32 v[20:21], v[20:21], v[164:165]
	v_pk_mul_f32 v[22:23], v[22:23], v[166:167]
	v_pk_mul_f32 v[24:25], v[24:25], v[168:169]
	v_pk_mul_f32 v[26:27], v[26:27], v[170:171]
	v_pk_mul_f32 v[28:29], v[28:29], v[172:173]
	v_pk_mul_f32 v[30:31], v[30:31], v[174:175]
	v_pk_mul_f32 v[32:33], v[32:33], v[160:161]
	v_pk_mul_f32 v[34:35], v[34:35], v[162:163]
	v_pk_mul_f32 v[36:37], v[36:37], v[164:165]
	v_pk_mul_f32 v[38:39], v[38:39], v[166:167]
	v_pk_mul_f32 v[40:41], v[40:41], v[168:169]
	v_pk_mul_f32 v[42:43], v[42:43], v[170:171]
	v_pk_mul_f32 v[44:45], v[44:45], v[172:173]
	v_pk_mul_f32 v[46:47], v[46:47], v[174:175]
	v_pk_mul_f32 v[48:49], v[48:49], v[160:161]
	v_pk_mul_f32 v[50:51], v[50:51], v[162:163]
	v_pk_mul_f32 v[52:53], v[52:53], v[164:165]
	v_pk_mul_f32 v[54:55], v[54:55], v[166:167]
	v_pk_mul_f32 v[56:57], v[56:57], v[168:169]
	v_pk_mul_f32 v[58:59], v[58:59], v[170:171]
	v_pk_mul_f32 v[60:61], v[60:61], v[172:173]
	v_pk_mul_f32 v[62:63], v[62:63], v[174:175]
	v_sub_f32_e32 v64, v253, v149
	v_mov_b32_e32 v220, v64
	v_mov_b32_e32 v221, v64
	v_mov_b32_e32 v222, v64
	v_mov_b32_e32 v223, v64
	v_mov_b32_e32 v224, v64
	v_mov_b32_e32 v225, v64
	v_mov_b32_e32 v226, v64
	v_mov_b32_e32 v227, v64
	v_mov_b32_e32 v228, v64
	v_mov_b32_e32 v229, v64
	v_mov_b32_e32 v230, v64
	v_mov_b32_e32 v231, v64
	v_mov_b32_e32 v232, v64
	v_mov_b32_e32 v233, v64
	v_mov_b32_e32 v234, v64
	v_mov_b32_e32 v235, v64
	s_branch .Ldg_back0_9
